# attn1 prompt loop qb-split pipeline + half-wave rescale ballot on SALU (no cross-half permlane in hot path), no static setprio
# speedup vs baseline: 1.0379x; 1.0057x over previous
; #define LAS __attribute__((address_space(3)))
; template <int DQ, bool BIAS, bool TAIL>
; __device__ __forceinline__ void attn_item(const AttnItem& A, LAS unsigned char* lds, int wave_s_) {
;     ...
;         if (act) {
; #pragma unroll
;             for (int kbk = 0; kbk < 2; ++kbk) {
;                 __builtin_amdgcn_sched_barrier(0);
;                 f32x16 s[2];
;                 s[0] = MFMA32(kf[0], qf[0][0], zero16v); s[1] = MFMA32(kf[0], qf[1][0], zero16v);
; #pragma unroll
;                 for (int kk = 1; kk < NKK; ++kk) { s[0] = MFMA32(kf[kk], qf[0][kk], s[0]); s[1] = MFMA32(kf[kk], qf[1][kk], s[1]); }
;                 s16x4 vlo[2][2], vhi[2][2];
; #pragma unroll
;                 for (int st = 0; st < 2; ++st)
; #pragma unroll
;                     for (int d = 0; d < 2; ++d) { const LAS unsigned char* vp = vb + ((32 * kbk + 16 * st) * VROW + 32 * d) * 2; vlo[st][d] = vtr(vp); vhi[st][d] = vtr(vp + 8 * VROW * 2); }
;                 __builtin_amdgcn_sched_barrier(0);
;                 float mx[2];
; #pragma unroll
;                 for (int qb = 0; qb < 2; ++qb) {
;                     if (BIAS || TAIL) {
;                         const int qk = A.q_kidx0 + 64 * w + 32 * qb + r32;
; #pragma unroll
;                         for (int i = 0; i < 16; ++i) { const int kidx = 64 * t + 32 * kbk + crow(i, hi);
;                             float v = s[qb][i]; if (BIAS) v += lut[kidx - qk + LUT0]; if (TAIL && kidx >= A.nkeys) v = -1.0e30f; s[qb][i] = v; }
;                     }
;                     const float t0 = max3f(s[qb][0], s[qb][1], s[qb][2]), t1 = max3f(s[qb][3], s[qb][4], s[qb][5]), t2 = max3f(s[qb][6], s[qb][7], s[qb][8]),
;                                 t3 = max3f(s[qb][9], s[qb][10], s[qb][11]), t4 = max3f(s[qb][12], s[qb][13], s[qb][14]);
;                     const float m = max3f(max3f(t0, t1, t2), max3f(t3, t4, s[qb][15]), t0);
;                     mx[qb] = swapmax(m, hi) - mref[qb];
;                 }
;                 const bool need0 = first || mx[0] > RESCALE_THR, need1 = first || mx[1] > RESCALE_THR;
;                 if (__builtin_amdgcn_ballot_w64(need0 || need1) != 0ull) {
; #pragma unroll
;                     for (int qb = 0; qb < 2; ++qb) {
;                         const float delta = (qb == 0 ? need0 : need1) ? mx[qb] : 0.f, alpha = __builtin_amdgcn_exp2f(-delta);
; #pragma unroll
.LBB0_1478:
	s_or_b64 exec, exec, s[10:11]
	s_andn2_b64 vcc, exec, s[8:9]
	s_cbranch_vccnz .LBB0_1484
	s_mul_i32 s8, s21, 0x2400
	v_add_u32_e32 v229, s8, v227
	s_waitcnt lgkmcnt(5)
	v_mfma_f32_32x32x16_bf16 v[80:95], v[176:179], v[96:99], 0
	ds_read_b64_tr_b16 v[192:193], v229 offset:26624
	ds_read_b64_tr_b16 v[194:195], v229 offset:27776
	ds_read_b64_tr_b16 v[188:189], v229 offset:26688
	ds_read_b64_tr_b16 v[190:191], v229 offset:27840
	ds_read_b64_tr_b16 v[184:185], v229 offset:28928
	ds_read_b64_tr_b16 v[186:187], v229 offset:30080
	ds_read_b64_tr_b16 v[180:181], v229 offset:28992
	ds_read_b64_tr_b16 v[182:183], v229 offset:30144
	s_waitcnt lgkmcnt(12)
	v_mfma_f32_32x32x16_bf16 v[80:95], v[172:175], v[100:103], v[80:95]
	s_waitcnt lgkmcnt(11)
	v_mfma_f32_32x32x16_bf16 v[80:95], v[168:171], v[104:107], v[80:95]
	s_waitcnt lgkmcnt(10)
	v_mfma_f32_32x32x16_bf16 v[80:95], v[164:167], v[108:111], v[80:95]
	s_waitcnt lgkmcnt(9)
	v_mfma_f32_32x32x16_bf16 v[80:95], v[160:163], v[112:115], v[80:95]
	s_waitcnt lgkmcnt(8)
	v_mfma_f32_32x32x16_bf16 v[80:95], v[156:159], v[116:119], v[80:95]
	v_mfma_f32_32x32x16_bf16 v[64:79], v[176:179], v[120:123], 0
	ds_read_b128 v[230:233], v196 offset:6656
	ds_read_b128 v[238:241], v196 offset:6688
	ds_read_b128 v[246:249], v196 offset:6720
	ds_read_b128 v[250:253], v196 offset:6752
	ds_read_b128 v[176:179], v196 offset:6784
	v_mfma_f32_32x32x16_bf16 v[64:79], v[172:175], v[124:127], v[64:79]
	ds_read_b128 v[172:175], v196 offset:6816
	s_nop 3
	v_max3_f32 v198, v80, v81, v82
	v_max3_f32 v199, v83, v84, v85
	v_max3_f32 v204, v86, v87, v88
	v_max3_f32 v205, v89, v90, v91
	v_max3_f32 v234, v92, v93, v94
	v_max3_f32 v199, v198, v199, v204
	v_max3_f32 v205, v205, v234, v95
	v_max3_f32 v204, v199, v205, v198
	v_mfma_f32_32x32x16_bf16 v[64:79], v[168:171], v[128:131], v[64:79]
	v_sub_f32_e32 v235, v204, v211
	v_cmp_lt_f32_e32 vcc, s81, v235
	s_or_b32 s8, vcc_lo, vcc_hi
	s_mov_b32 s9, s8
	s_or_b64 s[8:9], s[8:9], s[16:17]
	s_cbranch_scc1 .Lp4_rare_00
.Lp4_back_00:
	v_sub_f32_e32 v80, v80, v211
	v_sub_f32_e32 v81, v81, v211
	v_sub_f32_e32 v82, v82, v211
	v_sub_f32_e32 v83, v83, v211
	v_exp_f32_e32 v80, v80
	v_exp_f32_e32 v81, v81
	v_exp_f32_e32 v82, v82
	v_exp_f32_e32 v83, v83
	v_sub_f32_e32 v84, v84, v211
	v_sub_f32_e32 v85, v85, v211
	v_mfma_f32_32x32x16_bf16 v[64:79], v[164:167], v[132:135], v[64:79]
	v_sub_f32_e32 v86, v86, v211
	v_sub_f32_e32 v87, v87, v211
	v_exp_f32_e32 v84, v84
	v_exp_f32_e32 v85, v85
	v_exp_f32_e32 v86, v86
	v_exp_f32_e32 v87, v87
	v_add_f32_e32 v198, v80, v84
	v_add_f32_e32 v199, v81, v85
	v_add_f32_e32 v204, v82, v86
	v_add_f32_e32 v205, v83, v87
	v_sub_f32_e32 v88, v88, v211
	v_sub_f32_e32 v89, v89, v211
	v_mfma_f32_32x32x16_bf16 v[64:79], v[160:163], v[140:143], v[64:79]
	v_sub_f32_e32 v90, v90, v211
	v_sub_f32_e32 v91, v91, v211
	v_exp_f32_e32 v88, v88
	v_exp_f32_e32 v89, v89
	v_exp_f32_e32 v90, v90
	v_exp_f32_e32 v91, v91
	v_add_f32_e32 v198, v198, v88
	v_add_f32_e32 v199, v199, v89
	v_add_f32_e32 v204, v204, v90
	v_add_f32_e32 v205, v205, v91
	v_sub_f32_e32 v92, v92, v211
	v_sub_f32_e32 v93, v93, v211
	v_mfma_f32_32x32x16_bf16 v[64:79], v[156:159], v[136:139], v[64:79]
	v_sub_f32_e32 v94, v94, v211
	v_sub_f32_e32 v95, v95, v211
	v_exp_f32_e32 v92, v92
	v_exp_f32_e32 v93, v93
	v_exp_f32_e32 v94, v94
	v_exp_f32_e32 v95, v95
	v_cvt_pk_bf16_f32 v80, v80, v81
	v_add_f32_e32 v198, v198, v92
	v_add_f32_e32 v199, v199, v93
	v_add_f32_e32 v204, v204, v94
	v_add_f32_e32 v205, v205, v95
	v_cvt_pk_bf16_f32 v81, v82, v83
	v_add_f32_e32 v198, v198, v199
	v_add_f32_e32 v204, v204, v205
	v_cvt_pk_bf16_f32 v82, v84, v85
	v_add_f32_e32 v198, v198, v204
	v_cvt_pk_bf16_f32 v83, v86, v87
	v_add_f32_e32 v212, v212, v198
	v_cvt_pk_bf16_f32 v84, v88, v89
	v_cvt_pk_bf16_f32 v85, v90, v91
	v_cvt_pk_bf16_f32 v86, v92, v93
	v_cvt_pk_bf16_f32 v87, v94, v95
	v_max3_f32 v198, v64, v65, v66
	v_max3_f32 v199, v67, v68, v69
	v_max3_f32 v204, v70, v71, v72
	s_waitcnt lgkmcnt(12)
	v_mfma_f32_32x32x16_bf16 v[48:63], v[192:195], v[80:83], v[48:63]
	v_max3_f32 v205, v73, v74, v75
	v_max3_f32 v234, v76, v77, v78
	s_waitcnt lgkmcnt(10)
	v_mfma_f32_32x32x16_bf16 v[32:47], v[188:191], v[80:83], v[32:47]
	v_max3_f32 v199, v198, v199, v204
	v_max3_f32 v205, v205, v234, v79
	s_waitcnt lgkmcnt(8)
	v_mfma_f32_32x32x16_bf16 v[48:63], v[184:187], v[84:87], v[48:63]
	v_max3_f32 v204, v199, v205, v198
	v_sub_f32_e32 v235, v204, v223
	s_waitcnt lgkmcnt(6)
	v_mfma_f32_32x32x16_bf16 v[32:47], v[180:183], v[84:87], v[32:47]
	v_cmp_lt_f32_e32 vcc, s81, v235
	s_or_b32 s8, vcc_lo, vcc_hi
	s_mov_b32 s9, s8
	s_or_b64 s[8:9], s[8:9], s[100:101]
	s_cbranch_scc1 .Lp4_rare_01
; #define LAS __attribute__((address_space(3)))
; template <int DQ, bool BIAS, bool TAIL>
; __device__ __forceinline__ void attn_item(const AttnItem& A, LAS unsigned char* lds, int wave_s_) {
;     ...
;         if (act) {
; #pragma unroll
;             for (int kbk = 0; kbk < 2; ++kbk) {
;                 __builtin_amdgcn_sched_barrier(0);
;                 f32x16 s[2];
;                 s[0] = MFMA32(kf[0], qf[0][0], zero16v); s[1] = MFMA32(kf[0], qf[1][0], zero16v);
; #pragma unroll
;                 for (int kk = 1; kk < NKK; ++kk) { s[0] = MFMA32(kf[kk], qf[0][kk], s[0]); s[1] = MFMA32(kf[kk], qf[1][kk], s[1]); }
;                 s16x4 vlo[2][2], vhi[2][2];
; #pragma unroll
;                 for (int st = 0; st < 2; ++st)
; #pragma unroll
;                     for (int d = 0; d < 2; ++d) { const LAS unsigned char* vp = vb + ((32 * kbk + 16 * st) * VROW + 32 * d) * 2; vlo[st][d] = vtr(vp); vhi[st][d] = vtr(vp + 8 * VROW * 2); }
;                 __builtin_amdgcn_sched_barrier(0);
;                 float mx[2];
; #pragma unroll
;                 for (int qb = 0; qb < 2; ++qb) {
;                     if (BIAS || TAIL) {
;                         const int qk = A.q_kidx0 + 64 * w + 32 * qb + r32;
; #pragma unroll
;                         for (int i = 0; i < 16; ++i) { const int kidx = 64 * t + 32 * kbk + crow(i, hi);
;                             float v = s[qb][i]; if (BIAS) v += lut[kidx - qk + LUT0]; if (TAIL && kidx >= A.nkeys) v = -1.0e30f; s[qb][i] = v; }
;                     }
;                     const float t0 = max3f(s[qb][0], s[qb][1], s[qb][2]), t1 = max3f(s[qb][3], s[qb][4], s[qb][5]), t2 = max3f(s[qb][6], s[qb][7], s[qb][8]),
;                                 t3 = max3f(s[qb][9], s[qb][10], s[qb][11]), t4 = max3f(s[qb][12], s[qb][13], s[qb][14]);
;                     const float m = max3f(max3f(t0, t1, t2), max3f(t3, t4, s[qb][15]), t0);
;                     mx[qb] = swapmax(m, hi) - mref[qb];
;                 }
;                 const bool need0 = first || mx[0] > RESCALE_THR, need1 = first || mx[1] > RESCALE_THR;
;                 if (__builtin_amdgcn_ballot_w64(need0 || need1) != 0ull) {
; #pragma unroll
;                     for (int qb = 0; qb < 2; ++qb) {
;                         const float delta = (qb == 0 ? need0 : need1) ? mx[qb] : 0.f, alpha = __builtin_amdgcn_exp2f(-delta);
; #pragma unroll
.Lp4_back_01:
	v_sub_f32_e32 v64, v64, v223
	v_sub_f32_e32 v65, v65, v223
	v_sub_f32_e32 v66, v66, v223
	v_sub_f32_e32 v67, v67, v223
	s_waitcnt lgkmcnt(5)
	v_mfma_f32_32x32x16_bf16 v[80:95], v[230:233], v[96:99], 0
	v_exp_f32_e32 v64, v64
	v_exp_f32_e32 v65, v65
	v_exp_f32_e32 v66, v66
	v_exp_f32_e32 v67, v67
	v_sub_f32_e32 v68, v68, v223
	v_sub_f32_e32 v69, v69, v223
	v_sub_f32_e32 v70, v70, v223
	v_sub_f32_e32 v71, v71, v223
	s_waitcnt lgkmcnt(4)
	v_mfma_f32_32x32x16_bf16 v[80:95], v[238:241], v[100:103], v[80:95]
	v_exp_f32_e32 v68, v68
	v_exp_f32_e32 v69, v69
	v_exp_f32_e32 v70, v70
	v_exp_f32_e32 v71, v71
	v_add_f32_e32 v198, v64, v68
	v_add_f32_e32 v199, v65, v69
	v_add_f32_e32 v204, v66, v70
	v_add_f32_e32 v205, v67, v71
	s_waitcnt lgkmcnt(3)
	v_mfma_f32_32x32x16_bf16 v[80:95], v[246:249], v[104:107], v[80:95]
	v_sub_f32_e32 v72, v72, v223
	v_sub_f32_e32 v73, v73, v223
	v_sub_f32_e32 v74, v74, v223
	v_sub_f32_e32 v75, v75, v223
	v_exp_f32_e32 v72, v72
	v_exp_f32_e32 v73, v73
	v_exp_f32_e32 v74, v74
	v_exp_f32_e32 v75, v75
	s_waitcnt lgkmcnt(2)
	v_mfma_f32_32x32x16_bf16 v[80:95], v[250:253], v[108:111], v[80:95]
	v_add_f32_e32 v198, v198, v72
	v_add_f32_e32 v199, v199, v73
	v_add_f32_e32 v204, v204, v74
	v_add_f32_e32 v205, v205, v75
	v_sub_f32_e32 v76, v76, v223
	v_sub_f32_e32 v77, v77, v223
	v_sub_f32_e32 v78, v78, v223
	v_sub_f32_e32 v79, v79, v223
	s_waitcnt lgkmcnt(1)
	v_mfma_f32_32x32x16_bf16 v[80:95], v[176:179], v[112:115], v[80:95]
	v_exp_f32_e32 v76, v76
	v_exp_f32_e32 v77, v77
	v_exp_f32_e32 v78, v78
	v_exp_f32_e32 v79, v79
	v_cvt_pk_bf16_f32 v64, v64, v65
	v_add_f32_e32 v198, v198, v76
	v_add_f32_e32 v199, v199, v77
	s_waitcnt lgkmcnt(0)
	v_mfma_f32_32x32x16_bf16 v[80:95], v[172:175], v[116:119], v[80:95]
	v_add_f32_e32 v204, v204, v78
	v_add_f32_e32 v205, v205, v79
	v_cvt_pk_bf16_f32 v65, v66, v67
	v_add_f32_e32 v198, v198, v199
	v_add_f32_e32 v204, v204, v205
	v_cvt_pk_bf16_f32 v66, v68, v69
	v_add_f32_e32 v198, v198, v204
	v_cvt_pk_bf16_f32 v67, v70, v71
	v_add_f32_e32 v213, v213, v198
	v_cvt_pk_bf16_f32 v68, v72, v73
	v_cvt_pk_bf16_f32 v69, v74, v75
	v_cvt_pk_bf16_f32 v70, v76, v77
	v_cvt_pk_bf16_f32 v71, v78, v79
	v_max3_f32 v198, v80, v81, v82
	v_max3_f32 v199, v83, v84, v85
	v_max3_f32 v204, v86, v87, v88
	v_mfma_f32_32x32x16_bf16 v[16:31], v[192:195], v[64:67], v[16:31]
	v_max3_f32 v205, v89, v90, v91
	v_max3_f32 v234, v92, v93, v94
	v_mfma_f32_32x32x16_bf16 v[0:15], v[188:191], v[64:67], v[0:15]
	v_max3_f32 v199, v198, v199, v204
	v_max3_f32 v205, v205, v234, v95
	v_mfma_f32_32x32x16_bf16 v[16:31], v[184:187], v[68:71], v[16:31]
	v_max3_f32 v204, v199, v205, v198
	v_sub_f32_e32 v235, v204, v211
	v_mfma_f32_32x32x16_bf16 v[0:15], v[180:183], v[68:71], v[0:15]
	ds_read_b64_tr_b16 v[192:193], v229 offset:31232
	ds_read_b64_tr_b16 v[194:195], v229 offset:32384
	ds_read_b64_tr_b16 v[188:189], v229 offset:31296
	ds_read_b64_tr_b16 v[190:191], v229 offset:32448
	ds_read_b64_tr_b16 v[184:185], v229 offset:33536
	ds_read_b64_tr_b16 v[186:187], v229 offset:34688
	ds_read_b64_tr_b16 v[180:181], v229 offset:33600
	ds_read_b64_tr_b16 v[182:183], v229 offset:34752
	v_cmp_lt_f32_e32 vcc, s81, v235
	s_or_b32 s8, vcc_lo, vcc_hi
	s_mov_b32 s9, s8
	s_or_b64 s[8:9], s[8:9], s[16:17]
	s_cbranch_scc1 .Lp4_rare_10
.Lp4_back_10:
	v_sub_f32_e32 v80, v80, v211
	v_sub_f32_e32 v81, v81, v211
	v_sub_f32_e32 v82, v82, v211
	v_sub_f32_e32 v83, v83, v211
	v_mfma_f32_32x32x16_bf16 v[64:79], v[230:233], v[120:123], 0
	v_exp_f32_e32 v80, v80
	v_exp_f32_e32 v81, v81
	v_exp_f32_e32 v82, v82
	v_exp_f32_e32 v83, v83
	v_sub_f32_e32 v84, v84, v211
	v_sub_f32_e32 v85, v85, v211
	v_sub_f32_e32 v86, v86, v211
	v_sub_f32_e32 v87, v87, v211
	v_mfma_f32_32x32x16_bf16 v[64:79], v[238:241], v[124:127], v[64:79]
	v_exp_f32_e32 v84, v84
	v_exp_f32_e32 v85, v85
	v_exp_f32_e32 v86, v86
	v_exp_f32_e32 v87, v87
	v_add_f32_e32 v198, v80, v84
	v_add_f32_e32 v199, v81, v85
	v_add_f32_e32 v204, v82, v86
	v_add_f32_e32 v205, v83, v87
	v_mfma_f32_32x32x16_bf16 v[64:79], v[246:249], v[128:131], v[64:79]
	v_sub_f32_e32 v88, v88, v211
	v_sub_f32_e32 v89, v89, v211
	v_sub_f32_e32 v90, v90, v211
	v_sub_f32_e32 v91, v91, v211
	v_exp_f32_e32 v88, v88
	v_exp_f32_e32 v89, v89
	v_exp_f32_e32 v90, v90
	v_exp_f32_e32 v91, v91
	v_mfma_f32_32x32x16_bf16 v[64:79], v[250:253], v[132:135], v[64:79]
	v_add_f32_e32 v198, v198, v88
	v_add_f32_e32 v199, v199, v89
	v_add_f32_e32 v204, v204, v90
	v_add_f32_e32 v205, v205, v91
	v_sub_f32_e32 v92, v92, v211
	v_sub_f32_e32 v93, v93, v211
	v_sub_f32_e32 v94, v94, v211
	v_sub_f32_e32 v95, v95, v211
	v_mfma_f32_32x32x16_bf16 v[64:79], v[176:179], v[140:143], v[64:79]
	v_exp_f32_e32 v92, v92
	v_exp_f32_e32 v93, v93
	v_exp_f32_e32 v94, v94
	v_exp_f32_e32 v95, v95
	v_cvt_pk_bf16_f32 v80, v80, v81
	v_add_f32_e32 v198, v198, v92
	v_add_f32_e32 v199, v199, v93
	v_mfma_f32_32x32x16_bf16 v[64:79], v[172:175], v[136:139], v[64:79]
	v_add_f32_e32 v204, v204, v94
	v_add_f32_e32 v205, v205, v95
	v_cvt_pk_bf16_f32 v81, v82, v83
	v_add_f32_e32 v198, v198, v199
	v_add_f32_e32 v204, v204, v205
	v_cvt_pk_bf16_f32 v82, v84, v85
	v_add_f32_e32 v198, v198, v204
	v_cvt_pk_bf16_f32 v83, v86, v87
	v_add_f32_e32 v212, v212, v198
	v_cvt_pk_bf16_f32 v84, v88, v89
	v_cvt_pk_bf16_f32 v85, v90, v91
	v_cvt_pk_bf16_f32 v86, v92, v93
	v_cvt_pk_bf16_f32 v87, v94, v95
	v_max3_f32 v198, v64, v65, v66
	v_max3_f32 v199, v67, v68, v69
	v_max3_f32 v204, v70, v71, v72
	v_max3_f32 v205, v73, v74, v75
	v_max3_f32 v234, v76, v77, v78
	v_max3_f32 v199, v198, v199, v204
	v_max3_f32 v205, v205, v234, v79
	v_max3_f32 v204, v199, v205, v198
	v_sub_f32_e32 v235, v204, v223
	v_cmp_lt_f32_e32 vcc, s81, v235
	s_waitcnt lgkmcnt(6)
	v_mfma_f32_32x32x16_bf16 v[48:63], v[192:195], v[80:83], v[48:63]
	s_or_b32 s8, vcc_lo, vcc_hi
	s_mov_b32 s9, s8
	s_or_b64 s[8:9], s[8:9], s[100:101]
	s_cbranch_scc1 .Lp4_rare_11
; #define LAS __attribute__((address_space(3)))
; __device__ __forceinline__ unsigned pk2c(float lo, float hi) { f32x2_t v = {lo, hi}; bf16x2_t b = __builtin_convertvector(v, bf16x2_t); return __builtin_bit_cast(unsigned, b); }
; template <int DQ, bool BIAS, bool TAIL>
; __device__ __forceinline__ void attn_item(const AttnItem& A, LAS unsigned char* lds, int wave_s_) {
;     ...
;                 const bool need0 = first || mx[0] > RESCALE_THR, need1 = first || mx[1] > RESCALE_THR;
;                 if (__builtin_amdgcn_ballot_w64(need0 || need1) != 0ull) {
; #pragma unroll
;                     for (int qb = 0; qb < 2; ++qb) {
;                         const float delta = (qb == 0 ? need0 : need1) ? mx[qb] : 0.f, alpha = __builtin_amdgcn_exp2f(-delta);
; #pragma unroll
;                         for (int i = 0; i < 16; ++i) { o[0][qb][i] *= alpha; o[1][qb][i] *= alpha; }
;                         lrun[qb] *= alpha; mref[qb] += delta;
;                     }
;                     first = false;
;                 }
;     ...
;                 for (int qb = 0; qb < 2; ++qb) { float l4[4] = {0.f, 0.f, 0.f, 0.f};
; #pragma unroll
;                     for (int i = 0; i < 16; ++i) { const float pv = __builtin_amdgcn_exp2f(s[qb][i] - mref[qb]); s[qb][i] = pv; l4[i & 3] += pv; }
;                     lrun[qb] += (l4[0] + l4[1]) + (l4[2] + l4[3]); }
;                 bf16x8 pf[2][2];
; #pragma unroll
;                 for (int st = 0; st < 2; ++st)
; #pragma unroll
;                     for (int qb = 0; qb < 2; ++qb) { u32x4 pw;
; #pragma unroll
;                         for (int j = 0; j < 4; ++j) pw[j] = pk2c(s[qb][8 * st + 2 * j], s[qb][8 * st + 2 * j + 1]);
;                         pf[st][qb] = __builtin_bit_cast(bf16x8, pw); }
;                 if (kbk == 0) {
; #pragma unroll
;                     for (int kk = 0; kk < NKK; ++kk) kf[kk] = *(const LAS bf16x8*)(kb + (32 * KSTR + 16 * kk) * 2);
;                 }
;                 __builtin_amdgcn_sched_barrier(0);
; #pragma unroll
;                 for (int st = 0; st < 2; ++st)
; #pragma unroll
;                     for (int d = 0; d < 2; ++d) {
;                         const bf16x8 vf = __builtin_shufflevector(vlo[st][d], vhi[st][d], 0, 1, 2, 3, 4, 5, 6, 7);
;                         o[d][0] = MFMA32(vf, pf[st][0], o[d][0]);
;                         o[d][1] = MFMA32(vf, pf[st][1], o[d][1]);
;                     }
.Lp4_back_11:
	v_sub_f32_e32 v64, v64, v223
	v_sub_f32_e32 v65, v65, v223
	v_sub_f32_e32 v66, v66, v223
	v_sub_f32_e32 v67, v67, v223
	v_exp_f32_e32 v64, v64
	v_exp_f32_e32 v65, v65
	v_exp_f32_e32 v66, v66
	v_exp_f32_e32 v67, v67
	v_sub_f32_e32 v68, v68, v223
	v_sub_f32_e32 v69, v69, v223
	v_sub_f32_e32 v70, v70, v223
	v_sub_f32_e32 v71, v71, v223
	v_exp_f32_e32 v68, v68
	v_exp_f32_e32 v69, v69
	s_waitcnt lgkmcnt(4)
	v_mfma_f32_32x32x16_bf16 v[32:47], v[188:191], v[80:83], v[32:47]
	v_exp_f32_e32 v70, v70
	v_exp_f32_e32 v71, v71
	v_add_f32_e32 v198, v64, v68
	v_add_f32_e32 v199, v65, v69
	v_add_f32_e32 v204, v66, v70
	v_add_f32_e32 v205, v67, v71
	v_sub_f32_e32 v72, v72, v223
	v_sub_f32_e32 v73, v73, v223
	v_sub_f32_e32 v74, v74, v223
	v_sub_f32_e32 v75, v75, v223
	v_exp_f32_e32 v72, v72
	v_exp_f32_e32 v73, v73
	v_exp_f32_e32 v74, v74
	v_exp_f32_e32 v75, v75
	s_waitcnt lgkmcnt(2)
	v_mfma_f32_32x32x16_bf16 v[48:63], v[184:187], v[84:87], v[48:63]
	v_add_f32_e32 v198, v198, v72
	v_add_f32_e32 v199, v199, v73
	v_add_f32_e32 v204, v204, v74
	v_add_f32_e32 v205, v205, v75
	v_sub_f32_e32 v76, v76, v223
	v_sub_f32_e32 v77, v77, v223
	v_sub_f32_e32 v78, v78, v223
	v_sub_f32_e32 v79, v79, v223
	v_exp_f32_e32 v76, v76
	v_exp_f32_e32 v77, v77
	v_exp_f32_e32 v78, v78
	v_exp_f32_e32 v79, v79
	v_cvt_pk_bf16_f32 v64, v64, v65
	v_add_f32_e32 v198, v198, v76
	s_waitcnt lgkmcnt(0)
	v_mfma_f32_32x32x16_bf16 v[32:47], v[180:183], v[84:87], v[32:47]
	v_add_f32_e32 v199, v199, v77
	v_add_f32_e32 v204, v204, v78
	v_add_f32_e32 v205, v205, v79
	v_cvt_pk_bf16_f32 v65, v66, v67
	v_add_f32_e32 v198, v198, v199
	v_add_f32_e32 v204, v204, v205
	v_cvt_pk_bf16_f32 v66, v68, v69
	v_add_f32_e32 v198, v198, v204
	v_cvt_pk_bf16_f32 v67, v70, v71
	v_add_f32_e32 v213, v213, v198
	v_cvt_pk_bf16_f32 v68, v72, v73
	v_cvt_pk_bf16_f32 v69, v74, v75
	v_cvt_pk_bf16_f32 v70, v76, v77
	v_cvt_pk_bf16_f32 v71, v78, v79
	s_nop 1
	v_mfma_f32_32x32x16_bf16 v[16:31], v[192:195], v[64:67], v[16:31]
	v_mfma_f32_32x32x16_bf16 v[0:15], v[188:191], v[64:67], v[0:15]
	v_mfma_f32_32x32x16_bf16 v[16:31], v[184:187], v[68:71], v[16:31]
	v_mfma_f32_32x32x16_bf16 v[0:15], v[180:183], v[68:71], v[0:15]
	s_branch .LBB0_1484
.Lp4_rare_00:
	s_nop 15
	v_mov_b32_e32 v234, v204
	s_nop 1
	v_permlane32_swap_b32_e32 v234, v204
	v_max_f32_e32 v198, v234, v204
	v_sub_f32_e32 v235, v198, v211
	v_cndmask_b32_e64 v234, 0, v235, s[8:9]
	v_exp_f32_e64 v198, -v234
	v_add_f32_e32 v211, v211, v234
	s_nop 0
	v_pk_mul_f32 v[62:63], v[62:63], v[198:199] op_sel_hi:[1,0]
	v_pk_mul_f32 v[60:61], v[60:61], v[198:199] op_sel_hi:[1,0]
	v_pk_mul_f32 v[58:59], v[58:59], v[198:199] op_sel_hi:[1,0]
	v_pk_mul_f32 v[56:57], v[56:57], v[198:199] op_sel_hi:[1,0]
	v_pk_mul_f32 v[54:55], v[54:55], v[198:199] op_sel_hi:[1,0]
	v_pk_mul_f32 v[52:53], v[52:53], v[198:199] op_sel_hi:[1,0]
	v_pk_mul_f32 v[50:51], v[50:51], v[198:199] op_sel_hi:[1,0]
	v_pk_mul_f32 v[48:49], v[48:49], v[198:199] op_sel_hi:[1,0]
	v_pk_mul_f32 v[46:47], v[46:47], v[198:199] op_sel_hi:[1,0]
	v_pk_mul_f32 v[44:45], v[44:45], v[198:199] op_sel_hi:[1,0]
	v_pk_mul_f32 v[42:43], v[42:43], v[198:199] op_sel_hi:[1,0]
	v_pk_mul_f32 v[40:41], v[40:41], v[198:199] op_sel_hi:[1,0]
	v_pk_mul_f32 v[38:39], v[38:39], v[198:199] op_sel_hi:[1,0]
	v_pk_mul_f32 v[36:37], v[36:37], v[198:199] op_sel_hi:[1,0]
	v_pk_mul_f32 v[34:35], v[34:35], v[198:199] op_sel_hi:[1,0]
	v_pk_mul_f32 v[32:33], v[32:33], v[198:199] op_sel_hi:[1,0]
	v_mul_f32_e32 v212, v212, v198
	s_mov_b64 s[16:17], 0
	s_branch .Lp4_back_00
.Lp4_rare_01:
	s_nop 15
	v_mov_b32_e32 v234, v204
	s_nop 1
	v_permlane32_swap_b32_e32 v234, v204
	v_max_f32_e32 v198, v234, v204
	v_sub_f32_e32 v235, v198, v223
	v_cndmask_b32_e64 v234, 0, v235, s[8:9]
	v_exp_f32_e64 v198, -v234
	v_add_f32_e32 v223, v223, v234
	s_nop 0
	v_pk_mul_f32 v[30:31], v[30:31], v[198:199] op_sel_hi:[1,0]
	v_pk_mul_f32 v[28:29], v[28:29], v[198:199] op_sel_hi:[1,0]
	v_pk_mul_f32 v[26:27], v[26:27], v[198:199] op_sel_hi:[1,0]
	v_pk_mul_f32 v[24:25], v[24:25], v[198:199] op_sel_hi:[1,0]
	v_pk_mul_f32 v[22:23], v[22:23], v[198:199] op_sel_hi:[1,0]
	v_pk_mul_f32 v[20:21], v[20:21], v[198:199] op_sel_hi:[1,0]
	v_pk_mul_f32 v[18:19], v[18:19], v[198:199] op_sel_hi:[1,0]
	v_pk_mul_f32 v[16:17], v[16:17], v[198:199] op_sel_hi:[1,0]
	v_pk_mul_f32 v[14:15], v[14:15], v[198:199] op_sel_hi:[1,0]
	v_pk_mul_f32 v[12:13], v[12:13], v[198:199] op_sel_hi:[1,0]
	v_pk_mul_f32 v[10:11], v[10:11], v[198:199] op_sel_hi:[1,0]
	v_pk_mul_f32 v[8:9], v[8:9], v[198:199] op_sel_hi:[1,0]
	v_pk_mul_f32 v[6:7], v[6:7], v[198:199] op_sel_hi:[1,0]
	v_pk_mul_f32 v[4:5], v[4:5], v[198:199] op_sel_hi:[1,0]
	v_pk_mul_f32 v[2:3], v[2:3], v[198:199] op_sel_hi:[1,0]
	v_pk_mul_f32 v[0:1], v[0:1], v[198:199] op_sel_hi:[1,0]
	v_mul_f32_e32 v213, v213, v198
	s_mov_b64 s[100:101], 0
	s_branch .Lp4_back_01
